# v17 + same permlane-swap row reduction in the PH5 and PH11 residual epilogues (all four EpiRes epilogues now avoid ds_bpermute)
# speedup vs baseline: 1.0075x; 1.0075x over previous
.LBB0_1153:
	v_lshl_add_u32 v146, s38, 8, v148
	v_lshl_or_b32 v144, s36, 8, v150
	v_ashrrev_i32_e32 v147, 31, v146
	v_ashrrev_i32_e32 v145, 31, v144
	v_lshlrev_b64 v[156:157], 10, v[146:147]
	v_lshl_add_u64 v[156:157], v[156:157], 0, v[144:145]
	v_lshlrev_b64 v[160:161], 1, v[156:157]
	v_lshl_add_u64 v[156:157], s[16:17], 0, v[160:161]
	flat_load_dwordx4 v[156:159], v[156:157]
	v_lshl_add_u64 v[162:163], s[50:51], 0, v[160:161]
	v_or_b32_e32 v160, 0x100, v160
	v_lshl_add_u64 v[160:161], s[16:17], 0, v[160:161]
	v_xor_b32_e32 v155, 32, v154
	s_waitcnt vmcnt(0) lgkmcnt(0)
	v_lshlrev_b32_e32 v164, 16, v156
	v_and_b32_e32 v165, 0xffff0000, v156
	v_lshlrev_b32_e32 v156, 16, v157
	v_and_b32_e32 v157, 0xffff0000, v157
	v_lshlrev_b32_e32 v166, 16, v158
	v_and_b32_e32 v167, 0xffff0000, v158
	v_lshlrev_b32_e32 v158, 16, v159
	v_and_b32_e32 v159, 0xffff0000, v159
	v_pk_add_f32 v[126:127], v[126:127], v[156:157]
	v_pk_add_f32 v[156:157], v[124:125], v[164:165]
	v_pk_add_f32 v[158:159], v[122:123], v[158:159]
	v_pk_add_f32 v[164:165], v[120:121], v[166:167]
	v_cvt_pk_bf16_f32 v120, v156, v157
	v_cvt_pk_bf16_f32 v121, v126, v127
	v_cvt_pk_bf16_f32 v122, v164, v165
	v_cvt_pk_bf16_f32 v123, v158, v159
	global_store_dwordx4 v[162:163], v[120:123], off
	flat_load_dwordx4 v[122:125], v[160:161]
	v_mul_f32_e32 v157, v157, v157
	v_mul_f32_e32 v127, v127, v127
	v_mul_f32_e32 v160, v165, v165
	v_mul_f32_e32 v159, v159, v159
	v_fmac_f32_e32 v157, v156, v156
	v_fmac_f32_e32 v127, v126, v126
	v_fmac_f32_e32 v160, v164, v164
	v_fmac_f32_e32 v159, v158, v158
	v_add_f32_e32 v126, v157, v127
	v_add_f32_e32 v127, v160, v159
	v_add_f32_e32 v158, v126, v127
	v_and_b32_e32 v121, 64, v154
	v_xor_b32_e32 v120, 16, v154
	v_add_u32_e32 v121, 64, v121
	v_cmp_lt_i32_e32 vcc, v120, v121
	s_waitcnt vmcnt(0) lgkmcnt(0)
	v_lshlrev_b32_e32 v126, 16, v122
	v_and_b32_e32 v127, 0xffff0000, v122
	v_lshlrev_b32_e32 v122, 16, v123
	v_and_b32_e32 v123, 0xffff0000, v123
	v_lshlrev_b32_e32 v156, 16, v124
	v_and_b32_e32 v157, 0xffff0000, v124
	v_lshlrev_b32_e32 v124, 16, v125
	v_and_b32_e32 v125, 0xffff0000, v125
	v_pk_add_f32 v[118:119], v[118:119], v[122:123]
	v_pk_add_f32 v[116:117], v[116:117], v[126:127]
	v_pk_add_f32 v[122:123], v[114:115], v[124:125]
	v_pk_add_f32 v[124:125], v[112:113], v[156:157]
	v_mul_f32_e32 v112, v117, v117
	v_mul_f32_e32 v113, v119, v119
	v_mul_f32_e32 v114, v125, v125
	v_mul_f32_e32 v115, v123, v123
	v_fmac_f32_e32 v112, v116, v116
	v_fmac_f32_e32 v113, v118, v118
	v_fmac_f32_e32 v114, v124, v124
	v_fmac_f32_e32 v115, v122, v122
	v_add_f32_e32 v112, v112, v113
	v_add_f32_e32 v113, v114, v115
	v_cndmask_b32_e32 v120, v154, v120, vcc
	v_add_f32_e32 v112, v112, v113
	v_lshlrev_b32_e32 v120, 2, v120
	v_add_f32_e32 v112, v158, v112
	v_mov_b32_e32 v113, v112
	v_cmp_lt_i32_e32 vcc, v155, v121
	v_cvt_pk_bf16_f32 v116, v116, v117
	v_cvt_pk_bf16_f32 v117, v118, v119
	v_cndmask_b32_e32 v114, v154, v155, vcc
	v_lshlrev_b32_e32 v114, 2, v114
	v_permlane16_swap_b32_e32 v112, v113
	v_add_f32_e32 v112, v112, v113
	v_mov_b32_e32 v113, v112
	v_cvt_pk_bf16_f32 v118, v124, v125
	v_cvt_pk_bf16_f32 v119, v122, v123
	global_store_dwordx4 v[162:163], v[116:119], off offset:256
	v_permlane32_swap_b32_e32 v112, v113
	s_and_saveexec_b64 s[36:37], s[4:5]
	s_cbranch_execz .LBB0_1155
	v_lshl_add_u64 v[116:117], v[146:147], 2, s[14:15]
	s_nop 0
	v_add_f32_e32 v112, v112, v113
	flat_atomic_add_f32 v[116:117], v112
.LBB0_1155:
	s_or_b64 exec, exec, s[36:37]
	v_or_b32_e32 v112, 16, v146
	s_waitcnt lgkmcnt(0)
	v_ashrrev_i32_e32 v113, 31, v112
	v_lshlrev_b64 v[116:117], 10, v[112:113]
	v_lshl_add_u64 v[116:117], v[116:117], 0, v[144:145]
	v_lshlrev_b64 v[122:123], 1, v[116:117]
	v_lshl_add_u64 v[116:117], s[16:17], 0, v[122:123]
	flat_load_dwordx4 v[116:119], v[116:117]
	v_lshl_add_u64 v[124:125], s[50:51], 0, v[122:123]
	v_or_b32_e32 v122, 0x100, v122
	v_lshl_add_u64 v[122:123], s[16:17], 0, v[122:123]
	s_waitcnt vmcnt(0) lgkmcnt(0)
	v_lshlrev_b32_e32 v126, 16, v116
	v_and_b32_e32 v127, 0xffff0000, v116
	v_lshlrev_b32_e32 v116, 16, v117
	v_and_b32_e32 v117, 0xffff0000, v117
	v_lshlrev_b32_e32 v156, 16, v118
	v_and_b32_e32 v157, 0xffff0000, v118
	v_lshlrev_b32_e32 v118, 16, v119
	v_and_b32_e32 v119, 0xffff0000, v119
	v_pk_add_f32 v[110:111], v[110:111], v[116:117]
	v_pk_add_f32 v[108:109], v[108:109], v[126:127]
	v_pk_add_f32 v[116:117], v[106:107], v[118:119]
	v_pk_add_f32 v[118:119], v[104:105], v[156:157]
	v_cvt_pk_bf16_f32 v104, v108, v109
	v_cvt_pk_bf16_f32 v105, v110, v111
	v_cvt_pk_bf16_f32 v106, v118, v119
	v_cvt_pk_bf16_f32 v107, v116, v117
	global_store_dwordx4 v[124:125], v[104:107], off
	flat_load_dwordx4 v[104:107], v[122:123]
	v_mul_f32_e32 v109, v109, v109
	v_mul_f32_e32 v111, v111, v111
	v_mul_f32_e32 v115, v119, v119
	v_mul_f32_e32 v117, v117, v117
	v_fmac_f32_e32 v109, v108, v108
	v_fmac_f32_e32 v111, v110, v110
	v_fmac_f32_e32 v115, v118, v118
	v_fmac_f32_e32 v117, v116, v116
	v_add_f32_e32 v108, v109, v111
	v_add_f32_e32 v109, v115, v117
	v_add_f32_e32 v115, v108, v109
	s_waitcnt vmcnt(0) lgkmcnt(0)
	v_lshlrev_b32_e32 v108, 16, v104
	v_and_b32_e32 v109, 0xffff0000, v104
	v_lshlrev_b32_e32 v104, 16, v105
	v_and_b32_e32 v105, 0xffff0000, v105
	v_lshlrev_b32_e32 v110, 16, v106
	v_and_b32_e32 v111, 0xffff0000, v106
	v_lshlrev_b32_e32 v106, 16, v107
	v_and_b32_e32 v107, 0xffff0000, v107
	v_pk_add_f32 v[102:103], v[102:103], v[104:105]
	v_pk_add_f32 v[100:101], v[100:101], v[108:109]
	v_pk_add_f32 v[104:105], v[98:99], v[106:107]
	v_pk_add_f32 v[106:107], v[96:97], v[110:111]
	v_mul_f32_e32 v96, v101, v101
	v_mul_f32_e32 v97, v103, v103
	v_mul_f32_e32 v98, v107, v107
	v_mul_f32_e32 v99, v105, v105
	v_fmac_f32_e32 v96, v100, v100
	v_fmac_f32_e32 v97, v102, v102
	v_fmac_f32_e32 v98, v106, v106
	v_fmac_f32_e32 v99, v104, v104
	v_add_f32_e32 v96, v96, v97
	v_add_f32_e32 v97, v98, v99
	v_add_f32_e32 v96, v96, v97
	v_add_f32_e32 v96, v115, v96
	v_mov_b32_e32 v97, v96
	v_cvt_pk_bf16_f32 v98, v100, v101
	v_cvt_pk_bf16_f32 v99, v102, v103
	v_cvt_pk_bf16_f32 v100, v106, v107
	v_cvt_pk_bf16_f32 v101, v104, v105
	v_permlane16_swap_b32_e32 v96, v97
	v_add_f32_e32 v96, v96, v97
	v_mov_b32_e32 v97, v96
	global_store_dwordx4 v[124:125], v[98:101], off offset:256
	s_nop 0
	v_permlane32_swap_b32_e32 v96, v97
	s_and_saveexec_b64 s[36:37], s[4:5]
	s_cbranch_execz .LBB0_1157
	v_lshl_add_u64 v[98:99], v[112:113], 2, s[14:15]
	s_nop 0
	v_add_f32_e32 v96, v96, v97
	flat_atomic_add_f32 v[98:99], v96
.LBB0_1157:
	s_or_b64 exec, exec, s[36:37]
	v_or_b32_e32 v96, 32, v146
	s_waitcnt lgkmcnt(0)
	v_ashrrev_i32_e32 v97, 31, v96
	v_lshlrev_b64 v[98:99], 10, v[96:97]
	v_lshl_add_u64 v[98:99], v[98:99], 0, v[144:145]
	v_lshlrev_b64 v[102:103], 1, v[98:99]
	v_lshl_add_u64 v[98:99], s[16:17], 0, v[102:103]
	flat_load_dwordx4 v[98:101], v[98:99]
	v_lshl_add_u64 v[104:105], s[50:51], 0, v[102:103]
	v_or_b32_e32 v102, 0x100, v102
	v_lshl_add_u64 v[102:103], s[16:17], 0, v[102:103]
	s_waitcnt vmcnt(0) lgkmcnt(0)
	v_lshlrev_b32_e32 v106, 16, v98
	v_and_b32_e32 v107, 0xffff0000, v98
	v_lshlrev_b32_e32 v98, 16, v99
	v_and_b32_e32 v99, 0xffff0000, v99
	v_lshlrev_b32_e32 v108, 16, v100
	v_and_b32_e32 v109, 0xffff0000, v100
	v_lshlrev_b32_e32 v100, 16, v101
	v_and_b32_e32 v101, 0xffff0000, v101
	v_pk_add_f32 v[94:95], v[94:95], v[98:99]
	v_pk_add_f32 v[92:93], v[92:93], v[106:107]
	v_pk_add_f32 v[98:99], v[90:91], v[100:101]
	v_pk_add_f32 v[100:101], v[88:89], v[108:109]
	v_cvt_pk_bf16_f32 v88, v92, v93
	v_cvt_pk_bf16_f32 v89, v94, v95
	v_cvt_pk_bf16_f32 v90, v100, v101
	v_cvt_pk_bf16_f32 v91, v98, v99
	global_store_dwordx4 v[104:105], v[88:91], off
	flat_load_dwordx4 v[88:91], v[102:103]
	v_mul_f32_e32 v93, v93, v93
	v_mul_f32_e32 v95, v95, v95
	v_mul_f32_e32 v101, v101, v101
	v_mul_f32_e32 v99, v99, v99
	v_fmac_f32_e32 v93, v92, v92
	v_fmac_f32_e32 v95, v94, v94
	v_fmac_f32_e32 v101, v100, v100
	v_fmac_f32_e32 v99, v98, v98
	v_add_f32_e32 v92, v93, v95
	v_add_f32_e32 v93, v101, v99
	v_add_f32_e32 v98, v92, v93
	s_waitcnt vmcnt(0) lgkmcnt(0)
	v_lshlrev_b32_e32 v92, 16, v88
	v_and_b32_e32 v93, 0xffff0000, v88
	v_lshlrev_b32_e32 v88, 16, v89
	v_and_b32_e32 v89, 0xffff0000, v89
	v_lshlrev_b32_e32 v94, 16, v90
	v_and_b32_e32 v95, 0xffff0000, v90
	v_lshlrev_b32_e32 v90, 16, v91
	v_and_b32_e32 v91, 0xffff0000, v91
	v_pk_add_f32 v[86:87], v[86:87], v[88:89]
	v_pk_add_f32 v[84:85], v[84:85], v[92:93]
	v_pk_add_f32 v[88:89], v[82:83], v[90:91]
	v_pk_add_f32 v[90:91], v[80:81], v[94:95]
	v_mul_f32_e32 v80, v85, v85
	v_mul_f32_e32 v81, v87, v87
	v_mul_f32_e32 v82, v91, v91
	v_mul_f32_e32 v83, v89, v89
	v_fmac_f32_e32 v80, v84, v84
	v_fmac_f32_e32 v81, v86, v86
	v_fmac_f32_e32 v82, v90, v90
	v_fmac_f32_e32 v83, v88, v88
	v_add_f32_e32 v80, v80, v81
	v_add_f32_e32 v81, v82, v83
	v_add_f32_e32 v80, v80, v81
	v_add_f32_e32 v80, v98, v80
	v_mov_b32_e32 v81, v80
	v_cvt_pk_bf16_f32 v82, v84, v85
	v_cvt_pk_bf16_f32 v83, v86, v87
	v_cvt_pk_bf16_f32 v84, v90, v91
	v_cvt_pk_bf16_f32 v85, v88, v89
	v_permlane16_swap_b32_e32 v80, v81
	v_add_f32_e32 v80, v80, v81
	v_mov_b32_e32 v81, v80
	global_store_dwordx4 v[104:105], v[82:85], off offset:256
	s_nop 0
	v_permlane32_swap_b32_e32 v80, v81
	s_and_saveexec_b64 s[36:37], s[4:5]
	s_cbranch_execz .LBB0_1159
	v_lshl_add_u64 v[82:83], v[96:97], 2, s[14:15]
	s_nop 0
	v_add_f32_e32 v80, v80, v81
	flat_atomic_add_f32 v[82:83], v80
.LBB0_1159:
	s_or_b64 exec, exec, s[36:37]
	v_or_b32_e32 v80, 48, v146
	s_waitcnt lgkmcnt(0)
	v_ashrrev_i32_e32 v81, 31, v80
	v_lshlrev_b64 v[82:83], 10, v[80:81]
	v_lshl_add_u64 v[82:83], v[82:83], 0, v[144:145]
	v_lshlrev_b64 v[86:87], 1, v[82:83]
	v_lshl_add_u64 v[82:83], s[16:17], 0, v[86:87]
	flat_load_dwordx4 v[82:85], v[82:83]
	v_lshl_add_u64 v[88:89], s[50:51], 0, v[86:87]
	v_or_b32_e32 v86, 0x100, v86
	v_lshl_add_u64 v[86:87], s[16:17], 0, v[86:87]
	s_waitcnt vmcnt(0) lgkmcnt(0)
	v_lshlrev_b32_e32 v90, 16, v82
	v_and_b32_e32 v91, 0xffff0000, v82
	v_lshlrev_b32_e32 v82, 16, v83
	v_and_b32_e32 v83, 0xffff0000, v83
	v_lshlrev_b32_e32 v92, 16, v84
	v_and_b32_e32 v93, 0xffff0000, v84
	v_lshlrev_b32_e32 v84, 16, v85
	v_and_b32_e32 v85, 0xffff0000, v85
	v_pk_add_f32 v[78:79], v[78:79], v[82:83]
	v_pk_add_f32 v[76:77], v[76:77], v[90:91]
	v_pk_add_f32 v[82:83], v[74:75], v[84:85]
	v_pk_add_f32 v[84:85], v[72:73], v[92:93]
	v_cvt_pk_bf16_f32 v72, v76, v77
	v_cvt_pk_bf16_f32 v73, v78, v79
	v_cvt_pk_bf16_f32 v74, v84, v85
	v_cvt_pk_bf16_f32 v75, v82, v83
	global_store_dwordx4 v[88:89], v[72:75], off
	flat_load_dwordx4 v[72:75], v[86:87]
	v_mul_f32_e32 v77, v77, v77
	v_mul_f32_e32 v79, v79, v79
	v_mul_f32_e32 v85, v85, v85
	v_mul_f32_e32 v83, v83, v83
	v_fmac_f32_e32 v77, v76, v76
	v_fmac_f32_e32 v79, v78, v78
	v_fmac_f32_e32 v85, v84, v84
	v_fmac_f32_e32 v83, v82, v82
	v_add_f32_e32 v76, v77, v79
	v_add_f32_e32 v77, v85, v83
	v_add_f32_e32 v82, v76, v77
	s_waitcnt vmcnt(0) lgkmcnt(0)
	v_lshlrev_b32_e32 v76, 16, v72
	v_and_b32_e32 v77, 0xffff0000, v72
	v_lshlrev_b32_e32 v72, 16, v73
	v_and_b32_e32 v73, 0xffff0000, v73
	v_lshlrev_b32_e32 v78, 16, v74
	v_and_b32_e32 v79, 0xffff0000, v74
	v_lshlrev_b32_e32 v74, 16, v75
	v_and_b32_e32 v75, 0xffff0000, v75
	v_pk_add_f32 v[70:71], v[70:71], v[72:73]
	v_pk_add_f32 v[68:69], v[68:69], v[76:77]
	v_pk_add_f32 v[72:73], v[66:67], v[74:75]
	v_pk_add_f32 v[74:75], v[64:65], v[78:79]
	v_mul_f32_e32 v64, v69, v69
	v_mul_f32_e32 v65, v71, v71
	v_mul_f32_e32 v66, v75, v75
	v_mul_f32_e32 v67, v73, v73
	v_fmac_f32_e32 v64, v68, v68
	v_fmac_f32_e32 v65, v70, v70
	v_fmac_f32_e32 v66, v74, v74
	v_fmac_f32_e32 v67, v72, v72
	v_add_f32_e32 v64, v64, v65
	v_add_f32_e32 v65, v66, v67
	v_add_f32_e32 v64, v64, v65
	v_add_f32_e32 v64, v82, v64
	v_mov_b32_e32 v65, v64
	v_cvt_pk_bf16_f32 v66, v68, v69
	v_cvt_pk_bf16_f32 v67, v70, v71
	v_cvt_pk_bf16_f32 v68, v74, v75
	v_cvt_pk_bf16_f32 v69, v72, v73
	v_permlane16_swap_b32_e32 v64, v65
	v_add_f32_e32 v64, v64, v65
	v_mov_b32_e32 v65, v64
	global_store_dwordx4 v[88:89], v[66:69], off offset:256
	s_nop 0
	v_permlane32_swap_b32_e32 v64, v65
	s_and_saveexec_b64 s[36:37], s[4:5]
	s_cbranch_execz .LBB0_1161
	v_lshl_add_u64 v[66:67], v[80:81], 2, s[14:15]
	s_nop 0
	v_add_f32_e32 v64, v64, v65
	flat_atomic_add_f32 v[66:67], v64
.LBB0_1161:
	s_or_b64 exec, exec, s[36:37]
	v_add_u32_e32 v64, 0x80, v146
	s_waitcnt lgkmcnt(0)
	v_ashrrev_i32_e32 v65, 31, v64
	v_lshlrev_b64 v[66:67], 10, v[64:65]
	v_lshl_add_u64 v[66:67], v[66:67], 0, v[144:145]
	v_lshlrev_b64 v[70:71], 1, v[66:67]
	v_lshl_add_u64 v[66:67], s[16:17], 0, v[70:71]
	flat_load_dwordx4 v[66:69], v[66:67]
	v_lshl_add_u64 v[72:73], s[50:51], 0, v[70:71]
	v_or_b32_e32 v70, 0x100, v70
	v_lshl_add_u64 v[70:71], s[16:17], 0, v[70:71]
	s_waitcnt vmcnt(0) lgkmcnt(0)
	v_lshlrev_b32_e32 v74, 16, v66
	v_and_b32_e32 v75, 0xffff0000, v66
	v_lshlrev_b32_e32 v66, 16, v67
	v_and_b32_e32 v67, 0xffff0000, v67
	v_lshlrev_b32_e32 v76, 16, v68
	v_and_b32_e32 v77, 0xffff0000, v68
	v_lshlrev_b32_e32 v68, 16, v69
	v_and_b32_e32 v69, 0xffff0000, v69
	v_pk_add_f32 v[62:63], v[62:63], v[66:67]
	v_pk_add_f32 v[60:61], v[60:61], v[74:75]
	v_pk_add_f32 v[66:67], v[58:59], v[68:69]
	v_pk_add_f32 v[68:69], v[56:57], v[76:77]
	v_cvt_pk_bf16_f32 v56, v60, v61
	v_cvt_pk_bf16_f32 v57, v62, v63
	v_cvt_pk_bf16_f32 v58, v68, v69
	v_cvt_pk_bf16_f32 v59, v66, v67
	global_store_dwordx4 v[72:73], v[56:59], off
	flat_load_dwordx4 v[56:59], v[70:71]
	v_mul_f32_e32 v61, v61, v61
	v_mul_f32_e32 v63, v63, v63
	v_mul_f32_e32 v69, v69, v69
	v_mul_f32_e32 v67, v67, v67
	v_fmac_f32_e32 v61, v60, v60
	v_fmac_f32_e32 v63, v62, v62
	v_fmac_f32_e32 v69, v68, v68
	v_fmac_f32_e32 v67, v66, v66
	v_add_f32_e32 v60, v61, v63
	v_add_f32_e32 v61, v69, v67
	v_add_f32_e32 v66, v60, v61
	s_waitcnt vmcnt(0) lgkmcnt(0)
	v_lshlrev_b32_e32 v60, 16, v56
	v_and_b32_e32 v61, 0xffff0000, v56
	v_lshlrev_b32_e32 v56, 16, v57
	v_and_b32_e32 v57, 0xffff0000, v57
	v_lshlrev_b32_e32 v62, 16, v58
	v_and_b32_e32 v63, 0xffff0000, v58
	v_lshlrev_b32_e32 v58, 16, v59
	v_and_b32_e32 v59, 0xffff0000, v59
	v_pk_add_f32 v[54:55], v[54:55], v[56:57]
	v_pk_add_f32 v[52:53], v[52:53], v[60:61]
	v_pk_add_f32 v[56:57], v[50:51], v[58:59]
	v_pk_add_f32 v[58:59], v[48:49], v[62:63]
	v_mul_f32_e32 v48, v53, v53
	v_mul_f32_e32 v49, v55, v55
	v_mul_f32_e32 v50, v59, v59
	v_mul_f32_e32 v51, v57, v57
	v_fmac_f32_e32 v48, v52, v52
	v_fmac_f32_e32 v49, v54, v54
	v_fmac_f32_e32 v50, v58, v58
	v_fmac_f32_e32 v51, v56, v56
	v_add_f32_e32 v48, v48, v49
	v_add_f32_e32 v49, v50, v51
	v_add_f32_e32 v48, v48, v49
	v_add_f32_e32 v48, v66, v48
	v_mov_b32_e32 v49, v48
	v_cvt_pk_bf16_f32 v50, v52, v53
	v_cvt_pk_bf16_f32 v51, v54, v55
	v_cvt_pk_bf16_f32 v52, v58, v59
	v_cvt_pk_bf16_f32 v53, v56, v57
	v_permlane16_swap_b32_e32 v48, v49
	v_add_f32_e32 v48, v48, v49
	v_mov_b32_e32 v49, v48
	global_store_dwordx4 v[72:73], v[50:53], off offset:256
	s_nop 0
	v_permlane32_swap_b32_e32 v48, v49
	s_and_saveexec_b64 s[36:37], s[4:5]
	s_cbranch_execz .LBB0_1163
	v_lshl_add_u64 v[50:51], v[64:65], 2, s[14:15]
	s_nop 0
	v_add_f32_e32 v48, v48, v49
	flat_atomic_add_f32 v[50:51], v48
.LBB0_1163:
	s_or_b64 exec, exec, s[36:37]
	v_add_u32_e32 v48, 0x90, v146
	s_waitcnt lgkmcnt(0)
	v_ashrrev_i32_e32 v49, 31, v48
	v_lshlrev_b64 v[50:51], 10, v[48:49]
	v_lshl_add_u64 v[50:51], v[50:51], 0, v[144:145]
	v_lshlrev_b64 v[54:55], 1, v[50:51]
	v_lshl_add_u64 v[50:51], s[16:17], 0, v[54:55]
	flat_load_dwordx4 v[50:53], v[50:51]
	v_lshl_add_u64 v[56:57], s[50:51], 0, v[54:55]
	v_or_b32_e32 v54, 0x100, v54
	v_lshl_add_u64 v[54:55], s[16:17], 0, v[54:55]
	s_waitcnt vmcnt(0) lgkmcnt(0)
	v_lshlrev_b32_e32 v58, 16, v50
	v_and_b32_e32 v59, 0xffff0000, v50
	v_lshlrev_b32_e32 v50, 16, v51
	v_and_b32_e32 v51, 0xffff0000, v51
	v_lshlrev_b32_e32 v60, 16, v52
	v_and_b32_e32 v61, 0xffff0000, v52
	v_lshlrev_b32_e32 v52, 16, v53
	v_and_b32_e32 v53, 0xffff0000, v53
	v_pk_add_f32 v[46:47], v[46:47], v[50:51]
	v_pk_add_f32 v[44:45], v[44:45], v[58:59]
	v_pk_add_f32 v[50:51], v[42:43], v[52:53]
	v_pk_add_f32 v[52:53], v[40:41], v[60:61]
	v_cvt_pk_bf16_f32 v40, v44, v45
	v_cvt_pk_bf16_f32 v41, v46, v47
	v_cvt_pk_bf16_f32 v42, v52, v53
	v_cvt_pk_bf16_f32 v43, v50, v51
	global_store_dwordx4 v[56:57], v[40:43], off
	flat_load_dwordx4 v[40:43], v[54:55]
	v_mul_f32_e32 v45, v45, v45
	v_mul_f32_e32 v47, v47, v47
	v_mul_f32_e32 v53, v53, v53
	v_mul_f32_e32 v51, v51, v51
	v_fmac_f32_e32 v45, v44, v44
	v_fmac_f32_e32 v47, v46, v46
	v_fmac_f32_e32 v53, v52, v52
	v_fmac_f32_e32 v51, v50, v50
	v_add_f32_e32 v44, v45, v47
	v_add_f32_e32 v45, v53, v51
	v_add_f32_e32 v50, v44, v45
	s_waitcnt vmcnt(0) lgkmcnt(0)
	v_lshlrev_b32_e32 v44, 16, v40
	v_and_b32_e32 v45, 0xffff0000, v40
	v_lshlrev_b32_e32 v40, 16, v41
	v_and_b32_e32 v41, 0xffff0000, v41
	v_lshlrev_b32_e32 v46, 16, v42
	v_and_b32_e32 v47, 0xffff0000, v42
	v_lshlrev_b32_e32 v42, 16, v43
	v_and_b32_e32 v43, 0xffff0000, v43
	v_pk_add_f32 v[38:39], v[38:39], v[40:41]
	v_pk_add_f32 v[36:37], v[36:37], v[44:45]
	v_pk_add_f32 v[40:41], v[34:35], v[42:43]
	v_pk_add_f32 v[42:43], v[32:33], v[46:47]
	v_mul_f32_e32 v32, v37, v37
	v_mul_f32_e32 v33, v39, v39
	v_mul_f32_e32 v34, v43, v43
	v_mul_f32_e32 v35, v41, v41
	v_fmac_f32_e32 v32, v36, v36
	v_fmac_f32_e32 v33, v38, v38
	v_fmac_f32_e32 v34, v42, v42
	v_fmac_f32_e32 v35, v40, v40
	v_add_f32_e32 v32, v32, v33
	v_add_f32_e32 v33, v34, v35
	v_add_f32_e32 v32, v32, v33
	v_add_f32_e32 v32, v50, v32
	v_mov_b32_e32 v33, v32
	v_cvt_pk_bf16_f32 v34, v36, v37
	v_cvt_pk_bf16_f32 v35, v38, v39
	v_cvt_pk_bf16_f32 v36, v42, v43
	v_cvt_pk_bf16_f32 v37, v40, v41
	v_permlane16_swap_b32_e32 v32, v33
	v_add_f32_e32 v32, v32, v33
	v_mov_b32_e32 v33, v32
	global_store_dwordx4 v[56:57], v[34:37], off offset:256
	s_nop 0
	v_permlane32_swap_b32_e32 v32, v33
	s_and_saveexec_b64 s[36:37], s[4:5]
	s_cbranch_execz .LBB0_1165
	v_lshl_add_u64 v[34:35], v[48:49], 2, s[14:15]
	s_nop 0
	v_add_f32_e32 v32, v32, v33
	flat_atomic_add_f32 v[34:35], v32
.LBB0_1165:
	s_or_b64 exec, exec, s[36:37]
	v_add_u32_e32 v32, 0xa0, v146
	s_waitcnt lgkmcnt(0)
	v_ashrrev_i32_e32 v33, 31, v32
	v_lshlrev_b64 v[34:35], 10, v[32:33]
	v_lshl_add_u64 v[34:35], v[34:35], 0, v[144:145]
	v_lshlrev_b64 v[38:39], 1, v[34:35]
	v_lshl_add_u64 v[34:35], s[16:17], 0, v[38:39]
	flat_load_dwordx4 v[34:37], v[34:35]
	v_lshl_add_u64 v[40:41], s[50:51], 0, v[38:39]
	v_or_b32_e32 v38, 0x100, v38
	v_lshl_add_u64 v[38:39], s[16:17], 0, v[38:39]
	s_waitcnt vmcnt(0) lgkmcnt(0)
	v_lshlrev_b32_e32 v42, 16, v34
	v_and_b32_e32 v43, 0xffff0000, v34
	v_lshlrev_b32_e32 v34, 16, v35
	v_and_b32_e32 v35, 0xffff0000, v35
	v_lshlrev_b32_e32 v44, 16, v36
	v_and_b32_e32 v45, 0xffff0000, v36
	v_lshlrev_b32_e32 v36, 16, v37
	v_and_b32_e32 v37, 0xffff0000, v37
	v_pk_add_f32 v[30:31], v[30:31], v[34:35]
	v_pk_add_f32 v[28:29], v[28:29], v[42:43]
	v_pk_add_f32 v[34:35], v[26:27], v[36:37]
	v_pk_add_f32 v[36:37], v[24:25], v[44:45]
	v_cvt_pk_bf16_f32 v24, v28, v29
	v_cvt_pk_bf16_f32 v25, v30, v31
	v_cvt_pk_bf16_f32 v26, v36, v37
	v_cvt_pk_bf16_f32 v27, v34, v35
	global_store_dwordx4 v[40:41], v[24:27], off
	flat_load_dwordx4 v[24:27], v[38:39]
	v_mul_f32_e32 v29, v29, v29
	v_mul_f32_e32 v31, v31, v31
	v_mul_f32_e32 v37, v37, v37
	v_mul_f32_e32 v35, v35, v35
	v_fmac_f32_e32 v29, v28, v28
	v_fmac_f32_e32 v31, v30, v30
	v_fmac_f32_e32 v37, v36, v36
	v_fmac_f32_e32 v35, v34, v34
	v_add_f32_e32 v28, v29, v31
	v_add_f32_e32 v29, v37, v35
	v_add_f32_e32 v34, v28, v29
	s_waitcnt vmcnt(0) lgkmcnt(0)
	v_lshlrev_b32_e32 v28, 16, v24
	v_and_b32_e32 v29, 0xffff0000, v24
	v_lshlrev_b32_e32 v24, 16, v25
	v_and_b32_e32 v25, 0xffff0000, v25
	v_lshlrev_b32_e32 v30, 16, v26
	v_and_b32_e32 v31, 0xffff0000, v26
	v_lshlrev_b32_e32 v26, 16, v27
	v_and_b32_e32 v27, 0xffff0000, v27
	v_pk_add_f32 v[22:23], v[22:23], v[24:25]
	v_pk_add_f32 v[20:21], v[20:21], v[28:29]
	v_pk_add_f32 v[24:25], v[18:19], v[26:27]
	v_pk_add_f32 v[26:27], v[16:17], v[30:31]
	v_mul_f32_e32 v16, v21, v21
	v_mul_f32_e32 v17, v23, v23
	v_mul_f32_e32 v18, v27, v27
	v_mul_f32_e32 v19, v25, v25
	v_fmac_f32_e32 v16, v20, v20
	v_fmac_f32_e32 v17, v22, v22
	v_fmac_f32_e32 v18, v26, v26
	v_fmac_f32_e32 v19, v24, v24
	v_add_f32_e32 v16, v16, v17
	v_add_f32_e32 v17, v18, v19
	v_add_f32_e32 v16, v16, v17
	v_add_f32_e32 v16, v34, v16
	v_mov_b32_e32 v17, v16
	v_cvt_pk_bf16_f32 v18, v20, v21
	v_cvt_pk_bf16_f32 v19, v22, v23
	v_cvt_pk_bf16_f32 v20, v26, v27
	v_cvt_pk_bf16_f32 v21, v24, v25
	v_permlane16_swap_b32_e32 v16, v17
	v_add_f32_e32 v16, v16, v17
	v_mov_b32_e32 v17, v16
	global_store_dwordx4 v[40:41], v[18:21], off offset:256
	s_nop 0
	v_permlane32_swap_b32_e32 v16, v17
	s_and_saveexec_b64 s[36:37], s[4:5]
	s_cbranch_execz .LBB0_1167
	v_lshl_add_u64 v[18:19], v[32:33], 2, s[14:15]
	s_nop 0
	v_add_f32_e32 v16, v16, v17
	flat_atomic_add_f32 v[18:19], v16
.LBB0_1167:
	s_or_b64 exec, exec, s[36:37]
	v_add_u32_e32 v16, 0xb0, v146
	s_waitcnt lgkmcnt(0)
	v_ashrrev_i32_e32 v17, 31, v16
	v_lshlrev_b64 v[18:19], 10, v[16:17]
	v_lshl_add_u64 v[18:19], v[18:19], 0, v[144:145]
	v_lshlrev_b64 v[22:23], 1, v[18:19]
	v_lshl_add_u64 v[18:19], s[16:17], 0, v[22:23]
	flat_load_dwordx4 v[18:21], v[18:19]
	v_lshl_add_u64 v[24:25], s[50:51], 0, v[22:23]
	v_or_b32_e32 v22, 0x100, v22
	v_lshl_add_u64 v[22:23], s[16:17], 0, v[22:23]
	s_waitcnt vmcnt(0) lgkmcnt(0)
	v_lshlrev_b32_e32 v26, 16, v18
	v_and_b32_e32 v27, 0xffff0000, v18
	v_lshlrev_b32_e32 v18, 16, v19
	v_and_b32_e32 v19, 0xffff0000, v19
	v_lshlrev_b32_e32 v28, 16, v20
	v_and_b32_e32 v29, 0xffff0000, v20
	v_lshlrev_b32_e32 v20, 16, v21
	v_and_b32_e32 v21, 0xffff0000, v21
	v_pk_add_f32 v[14:15], v[14:15], v[18:19]
	v_pk_add_f32 v[12:13], v[12:13], v[26:27]
	v_pk_add_f32 v[18:19], v[10:11], v[20:21]
	v_pk_add_f32 v[20:21], v[8:9], v[28:29]
	v_cvt_pk_bf16_f32 v8, v12, v13
	v_cvt_pk_bf16_f32 v9, v14, v15
	v_cvt_pk_bf16_f32 v10, v20, v21
	v_cvt_pk_bf16_f32 v11, v18, v19
	global_store_dwordx4 v[24:25], v[8:11], off
	flat_load_dwordx4 v[8:11], v[22:23]
	v_mul_f32_e32 v13, v13, v13
	v_mul_f32_e32 v15, v15, v15
	v_mul_f32_e32 v21, v21, v21
	v_mul_f32_e32 v19, v19, v19
	v_fmac_f32_e32 v13, v12, v12
	v_fmac_f32_e32 v15, v14, v14
	v_fmac_f32_e32 v21, v20, v20
	v_fmac_f32_e32 v19, v18, v18
	v_add_f32_e32 v12, v13, v15
	v_add_f32_e32 v13, v21, v19
	v_add_f32_e32 v18, v12, v13
	s_waitcnt vmcnt(0) lgkmcnt(0)
	v_lshlrev_b32_e32 v12, 16, v8
	v_and_b32_e32 v13, 0xffff0000, v8
	v_lshlrev_b32_e32 v8, 16, v9
	v_and_b32_e32 v9, 0xffff0000, v9
	v_lshlrev_b32_e32 v14, 16, v10
	v_and_b32_e32 v15, 0xffff0000, v10
	v_lshlrev_b32_e32 v10, 16, v11
	v_and_b32_e32 v11, 0xffff0000, v11
	v_pk_add_f32 v[6:7], v[6:7], v[8:9]
	v_pk_add_f32 v[4:5], v[4:5], v[12:13]
	v_pk_add_f32 v[8:9], v[2:3], v[10:11]
	v_pk_add_f32 v[10:11], v[0:1], v[14:15]
	v_mul_f32_e32 v0, v5, v5
	v_mul_f32_e32 v1, v7, v7
	v_mul_f32_e32 v2, v11, v11
	v_mul_f32_e32 v3, v9, v9
	v_fmac_f32_e32 v0, v4, v4
	v_fmac_f32_e32 v1, v6, v6
	v_fmac_f32_e32 v2, v10, v10
	v_fmac_f32_e32 v3, v8, v8
	v_add_f32_e32 v0, v0, v1
	v_add_f32_e32 v1, v2, v3
	v_add_f32_e32 v0, v0, v1
	v_add_f32_e32 v0, v18, v0
	v_mov_b32_e32 v1, v0
	v_cvt_pk_bf16_f32 v2, v4, v5
	v_cvt_pk_bf16_f32 v3, v6, v7
	v_cvt_pk_bf16_f32 v4, v10, v11
	v_cvt_pk_bf16_f32 v5, v8, v9
	v_permlane16_swap_b32_e32 v0, v1
	v_add_f32_e32 v0, v0, v1
	v_mov_b32_e32 v1, v0
	global_store_dwordx4 v[24:25], v[2:5], off offset:256
	s_nop 0
	v_permlane32_swap_b32_e32 v0, v1
	s_and_saveexec_b64 s[36:37], s[4:5]
	s_cbranch_execz .LBB0_1169
	v_lshl_add_u64 v[2:3], v[16:17], 2, s[14:15]
	s_nop 0
	v_add_f32_e32 v0, v0, v1
	flat_atomic_add_f32 v[2:3], v0

.LBB0_1616:
	v_lshl_add_u32 v146, s56, 8, v148
	v_lshl_or_b32 v144, s26, 8, v150
	v_ashrrev_i32_e32 v147, 31, v146
	v_ashrrev_i32_e32 v145, 31, v144
	v_lshlrev_b64 v[154:155], 10, v[146:147]
	v_lshl_add_u64 v[154:155], v[154:155], 0, v[144:145]
	v_lshlrev_b64 v[158:159], 1, v[154:155]
	v_lshl_add_u64 v[160:161], s[50:51], 0, v[158:159]
	global_load_dwordx4 v[154:157], v[160:161], off
	v_lshl_add_u64 v[158:159], s[8:9], 0, v[158:159]
	v_xor_b32_e32 v153, 32, v152
	s_waitcnt vmcnt(0)
	v_lshlrev_b32_e32 v162, 16, v154
	v_and_b32_e32 v163, 0xffff0000, v154
	v_lshlrev_b32_e32 v154, 16, v155
	v_and_b32_e32 v155, 0xffff0000, v155
	v_lshlrev_b32_e32 v164, 16, v156
	v_and_b32_e32 v165, 0xffff0000, v156
	v_lshlrev_b32_e32 v156, 16, v157
	v_and_b32_e32 v157, 0xffff0000, v157
	v_pk_add_f32 v[126:127], v[126:127], v[154:155]
	v_pk_add_f32 v[154:155], v[124:125], v[162:163]
	v_pk_add_f32 v[156:157], v[122:123], v[156:157]
	v_pk_add_f32 v[162:163], v[120:121], v[164:165]
	v_cvt_pk_bf16_f32 v120, v154, v155
	v_cvt_pk_bf16_f32 v121, v126, v127
	v_cvt_pk_bf16_f32 v122, v162, v163
	v_cvt_pk_bf16_f32 v123, v156, v157
	flat_store_dwordx4 v[158:159], v[120:123]
	global_load_dwordx4 v[122:125], v[160:161], off offset:256
	v_mul_f32_e32 v155, v155, v155
	v_mul_f32_e32 v127, v127, v127
	v_mul_f32_e32 v160, v163, v163
	v_mul_f32_e32 v157, v157, v157
	v_fmac_f32_e32 v155, v154, v154
	v_fmac_f32_e32 v127, v126, v126
	v_fmac_f32_e32 v160, v162, v162
	v_fmac_f32_e32 v157, v156, v156
	v_add_f32_e32 v126, v155, v127
	v_add_f32_e32 v127, v160, v157
	v_add_f32_e32 v156, v126, v127
	v_and_b32_e32 v121, 64, v152
	v_xor_b32_e32 v120, 16, v152
	v_add_u32_e32 v121, 64, v121
	v_cmp_lt_i32_e32 vcc, v120, v121
	s_waitcnt vmcnt(0)
	v_lshlrev_b32_e32 v126, 16, v122
	v_and_b32_e32 v127, 0xffff0000, v122
	v_lshlrev_b32_e32 v122, 16, v123
	v_and_b32_e32 v123, 0xffff0000, v123
	v_lshlrev_b32_e32 v154, 16, v124
	v_and_b32_e32 v155, 0xffff0000, v124
	v_lshlrev_b32_e32 v124, 16, v125
	v_and_b32_e32 v125, 0xffff0000, v125
	v_pk_add_f32 v[118:119], v[118:119], v[122:123]
	v_pk_add_f32 v[116:117], v[116:117], v[126:127]
	v_pk_add_f32 v[122:123], v[114:115], v[124:125]
	v_pk_add_f32 v[124:125], v[112:113], v[154:155]
	v_mul_f32_e32 v112, v117, v117
	v_mul_f32_e32 v113, v119, v119
	v_mul_f32_e32 v114, v125, v125
	v_mul_f32_e32 v115, v123, v123
	v_fmac_f32_e32 v112, v116, v116
	v_fmac_f32_e32 v113, v118, v118
	v_fmac_f32_e32 v114, v124, v124
	v_fmac_f32_e32 v115, v122, v122
	v_add_f32_e32 v112, v112, v113
	v_add_f32_e32 v113, v114, v115
	v_cndmask_b32_e32 v120, v152, v120, vcc
	v_add_f32_e32 v112, v112, v113
	v_lshlrev_b32_e32 v120, 2, v120
	v_add_f32_e32 v112, v156, v112
	v_mov_b32_e32 v113, v112
	v_cmp_lt_i32_e32 vcc, v153, v121
	v_cvt_pk_bf16_f32 v116, v116, v117
	v_cvt_pk_bf16_f32 v117, v118, v119
	v_cndmask_b32_e32 v114, v152, v153, vcc
	v_lshlrev_b32_e32 v114, 2, v114
	v_permlane16_swap_b32_e32 v112, v113
	v_add_f32_e32 v112, v112, v113
	v_mov_b32_e32 v113, v112
	v_cvt_pk_bf16_f32 v118, v124, v125
	v_cvt_pk_bf16_f32 v119, v122, v123
	flat_store_dwordx4 v[158:159], v[116:119] offset:256
	v_permlane32_swap_b32_e32 v112, v113
	s_and_saveexec_b64 s[6:7], s[0:1]
	s_cbranch_execz .LBB0_1618
	v_lshl_add_u64 v[116:117], v[146:147], 2, s[14:15]
	s_nop 0
	v_add_f32_e32 v112, v112, v113
	flat_atomic_add_f32 v[116:117], v112
.LBB0_1618:
	s_or_b64 exec, exec, s[6:7]
	v_or_b32_e32 v112, 16, v146
	s_waitcnt lgkmcnt(0)
	v_ashrrev_i32_e32 v113, 31, v112
	v_lshlrev_b64 v[116:117], 10, v[112:113]
	v_lshl_add_u64 v[116:117], v[116:117], 0, v[144:145]
	v_lshlrev_b64 v[122:123], 1, v[116:117]
	v_lshl_add_u64 v[124:125], s[50:51], 0, v[122:123]
	global_load_dwordx4 v[116:119], v[124:125], off
	v_lshl_add_u64 v[122:123], s[8:9], 0, v[122:123]
	s_waitcnt vmcnt(0)
	v_lshlrev_b32_e32 v126, 16, v116
	v_and_b32_e32 v127, 0xffff0000, v116
	v_lshlrev_b32_e32 v116, 16, v117
	v_and_b32_e32 v117, 0xffff0000, v117
	v_lshlrev_b32_e32 v154, 16, v118
	v_and_b32_e32 v155, 0xffff0000, v118
	v_lshlrev_b32_e32 v118, 16, v119
	v_and_b32_e32 v119, 0xffff0000, v119
	v_pk_add_f32 v[110:111], v[110:111], v[116:117]
	v_pk_add_f32 v[108:109], v[108:109], v[126:127]
	v_pk_add_f32 v[116:117], v[106:107], v[118:119]
	v_pk_add_f32 v[118:119], v[104:105], v[154:155]
	v_cvt_pk_bf16_f32 v104, v108, v109
	v_cvt_pk_bf16_f32 v105, v110, v111
	v_cvt_pk_bf16_f32 v106, v118, v119
	v_cvt_pk_bf16_f32 v107, v116, v117
	flat_store_dwordx4 v[122:123], v[104:107]
	global_load_dwordx4 v[104:107], v[124:125], off offset:256
	v_mul_f32_e32 v109, v109, v109
	v_mul_f32_e32 v111, v111, v111
	v_mul_f32_e32 v115, v119, v119
	v_mul_f32_e32 v117, v117, v117
	v_fmac_f32_e32 v109, v108, v108
	v_fmac_f32_e32 v111, v110, v110
	v_fmac_f32_e32 v115, v118, v118
	v_fmac_f32_e32 v117, v116, v116
	v_add_f32_e32 v108, v109, v111
	v_add_f32_e32 v109, v115, v117
	v_add_f32_e32 v115, v108, v109
	s_waitcnt vmcnt(0)
	v_lshlrev_b32_e32 v108, 16, v104
	v_and_b32_e32 v109, 0xffff0000, v104
	v_lshlrev_b32_e32 v104, 16, v105
	v_and_b32_e32 v105, 0xffff0000, v105
	v_lshlrev_b32_e32 v110, 16, v106
	v_and_b32_e32 v111, 0xffff0000, v106
	v_lshlrev_b32_e32 v106, 16, v107
	v_and_b32_e32 v107, 0xffff0000, v107
	v_pk_add_f32 v[102:103], v[102:103], v[104:105]
	v_pk_add_f32 v[100:101], v[100:101], v[108:109]
	v_pk_add_f32 v[104:105], v[98:99], v[106:107]
	v_pk_add_f32 v[106:107], v[96:97], v[110:111]
	v_mul_f32_e32 v96, v101, v101
	v_mul_f32_e32 v97, v103, v103
	v_mul_f32_e32 v98, v107, v107
	v_mul_f32_e32 v99, v105, v105
	v_fmac_f32_e32 v96, v100, v100
	v_fmac_f32_e32 v97, v102, v102
	v_fmac_f32_e32 v98, v106, v106
	v_fmac_f32_e32 v99, v104, v104
	v_add_f32_e32 v96, v96, v97
	v_add_f32_e32 v97, v98, v99
	v_add_f32_e32 v96, v96, v97
	v_add_f32_e32 v96, v115, v96
	v_mov_b32_e32 v97, v96
	v_cvt_pk_bf16_f32 v98, v100, v101
	v_cvt_pk_bf16_f32 v99, v102, v103
	v_cvt_pk_bf16_f32 v100, v106, v107
	v_cvt_pk_bf16_f32 v101, v104, v105
	v_permlane16_swap_b32_e32 v96, v97
	v_add_f32_e32 v96, v96, v97
	v_mov_b32_e32 v97, v96
	flat_store_dwordx4 v[122:123], v[98:101] offset:256
	s_nop 0
	v_permlane32_swap_b32_e32 v96, v97
	s_and_saveexec_b64 s[6:7], s[0:1]
	s_cbranch_execz .LBB0_1620
	v_lshl_add_u64 v[98:99], v[112:113], 2, s[14:15]
	s_nop 0
	v_add_f32_e32 v96, v96, v97
	flat_atomic_add_f32 v[98:99], v96
.LBB0_1620:
	s_or_b64 exec, exec, s[6:7]
	v_or_b32_e32 v96, 32, v146
	s_waitcnt lgkmcnt(0)
	v_ashrrev_i32_e32 v97, 31, v96
	v_lshlrev_b64 v[98:99], 10, v[96:97]
	v_lshl_add_u64 v[98:99], v[98:99], 0, v[144:145]
	v_lshlrev_b64 v[102:103], 1, v[98:99]
	v_lshl_add_u64 v[104:105], s[50:51], 0, v[102:103]
	global_load_dwordx4 v[98:101], v[104:105], off
	v_lshl_add_u64 v[102:103], s[8:9], 0, v[102:103]
	s_waitcnt vmcnt(0)
	v_lshlrev_b32_e32 v106, 16, v98
	v_and_b32_e32 v107, 0xffff0000, v98
	v_lshlrev_b32_e32 v98, 16, v99
	v_and_b32_e32 v99, 0xffff0000, v99
	v_lshlrev_b32_e32 v108, 16, v100
	v_and_b32_e32 v109, 0xffff0000, v100
	v_lshlrev_b32_e32 v100, 16, v101
	v_and_b32_e32 v101, 0xffff0000, v101
	v_pk_add_f32 v[94:95], v[94:95], v[98:99]
	v_pk_add_f32 v[92:93], v[92:93], v[106:107]
	v_pk_add_f32 v[98:99], v[90:91], v[100:101]
	v_pk_add_f32 v[100:101], v[88:89], v[108:109]
	v_cvt_pk_bf16_f32 v88, v92, v93
	v_cvt_pk_bf16_f32 v89, v94, v95
	v_cvt_pk_bf16_f32 v90, v100, v101
	v_cvt_pk_bf16_f32 v91, v98, v99
	flat_store_dwordx4 v[102:103], v[88:91]
	global_load_dwordx4 v[88:91], v[104:105], off offset:256
	v_mul_f32_e32 v93, v93, v93
	v_mul_f32_e32 v95, v95, v95
	v_mul_f32_e32 v101, v101, v101
	v_mul_f32_e32 v99, v99, v99
	v_fmac_f32_e32 v93, v92, v92
	v_fmac_f32_e32 v95, v94, v94
	v_fmac_f32_e32 v101, v100, v100
	v_fmac_f32_e32 v99, v98, v98
	v_add_f32_e32 v92, v93, v95
	v_add_f32_e32 v93, v101, v99
	v_add_f32_e32 v98, v92, v93
	s_waitcnt vmcnt(0)
	v_lshlrev_b32_e32 v92, 16, v88
	v_and_b32_e32 v93, 0xffff0000, v88
	v_lshlrev_b32_e32 v88, 16, v89
	v_and_b32_e32 v89, 0xffff0000, v89
	v_lshlrev_b32_e32 v94, 16, v90
	v_and_b32_e32 v95, 0xffff0000, v90
	v_lshlrev_b32_e32 v90, 16, v91
	v_and_b32_e32 v91, 0xffff0000, v91
	v_pk_add_f32 v[86:87], v[86:87], v[88:89]
	v_pk_add_f32 v[84:85], v[84:85], v[92:93]
	v_pk_add_f32 v[88:89], v[82:83], v[90:91]
	v_pk_add_f32 v[90:91], v[80:81], v[94:95]
	v_mul_f32_e32 v80, v85, v85
	v_mul_f32_e32 v81, v87, v87
	v_mul_f32_e32 v82, v91, v91
	v_mul_f32_e32 v83, v89, v89
	v_fmac_f32_e32 v80, v84, v84
	v_fmac_f32_e32 v81, v86, v86
	v_fmac_f32_e32 v82, v90, v90
	v_fmac_f32_e32 v83, v88, v88
	v_add_f32_e32 v80, v80, v81
	v_add_f32_e32 v81, v82, v83
	v_add_f32_e32 v80, v80, v81
	v_add_f32_e32 v80, v98, v80
	v_mov_b32_e32 v81, v80
	v_cvt_pk_bf16_f32 v82, v84, v85
	v_cvt_pk_bf16_f32 v83, v86, v87
	v_cvt_pk_bf16_f32 v84, v90, v91
	v_cvt_pk_bf16_f32 v85, v88, v89
	v_permlane16_swap_b32_e32 v80, v81
	v_add_f32_e32 v80, v80, v81
	v_mov_b32_e32 v81, v80
	flat_store_dwordx4 v[102:103], v[82:85] offset:256
	s_nop 0
	v_permlane32_swap_b32_e32 v80, v81
	s_and_saveexec_b64 s[6:7], s[0:1]
	s_cbranch_execz .LBB0_1622
	v_lshl_add_u64 v[82:83], v[96:97], 2, s[14:15]
	s_nop 0
	v_add_f32_e32 v80, v80, v81
	flat_atomic_add_f32 v[82:83], v80
.LBB0_1622:
	s_or_b64 exec, exec, s[6:7]
	v_or_b32_e32 v80, 48, v146
	s_waitcnt lgkmcnt(0)
	v_ashrrev_i32_e32 v81, 31, v80
	v_lshlrev_b64 v[82:83], 10, v[80:81]
	v_lshl_add_u64 v[82:83], v[82:83], 0, v[144:145]
	v_lshlrev_b64 v[86:87], 1, v[82:83]
	v_lshl_add_u64 v[88:89], s[50:51], 0, v[86:87]
	global_load_dwordx4 v[82:85], v[88:89], off
	v_lshl_add_u64 v[86:87], s[8:9], 0, v[86:87]
	s_waitcnt vmcnt(0)
	v_lshlrev_b32_e32 v90, 16, v82
	v_and_b32_e32 v91, 0xffff0000, v82
	v_lshlrev_b32_e32 v82, 16, v83
	v_and_b32_e32 v83, 0xffff0000, v83
	v_lshlrev_b32_e32 v92, 16, v84
	v_and_b32_e32 v93, 0xffff0000, v84
	v_lshlrev_b32_e32 v84, 16, v85
	v_and_b32_e32 v85, 0xffff0000, v85
	v_pk_add_f32 v[78:79], v[78:79], v[82:83]
	v_pk_add_f32 v[76:77], v[76:77], v[90:91]
	v_pk_add_f32 v[82:83], v[74:75], v[84:85]
	v_pk_add_f32 v[84:85], v[72:73], v[92:93]
	v_cvt_pk_bf16_f32 v72, v76, v77
	v_cvt_pk_bf16_f32 v73, v78, v79
	v_cvt_pk_bf16_f32 v74, v84, v85
	v_cvt_pk_bf16_f32 v75, v82, v83
	flat_store_dwordx4 v[86:87], v[72:75]
	global_load_dwordx4 v[72:75], v[88:89], off offset:256
	v_mul_f32_e32 v77, v77, v77
	v_mul_f32_e32 v79, v79, v79
	v_mul_f32_e32 v85, v85, v85
	v_mul_f32_e32 v83, v83, v83
	v_fmac_f32_e32 v77, v76, v76
	v_fmac_f32_e32 v79, v78, v78
	v_fmac_f32_e32 v85, v84, v84
	v_fmac_f32_e32 v83, v82, v82
	v_add_f32_e32 v76, v77, v79
	v_add_f32_e32 v77, v85, v83
	v_add_f32_e32 v82, v76, v77
	s_waitcnt vmcnt(0)
	v_lshlrev_b32_e32 v76, 16, v72
	v_and_b32_e32 v77, 0xffff0000, v72
	v_lshlrev_b32_e32 v72, 16, v73
	v_and_b32_e32 v73, 0xffff0000, v73
	v_lshlrev_b32_e32 v78, 16, v74
	v_and_b32_e32 v79, 0xffff0000, v74
	v_lshlrev_b32_e32 v74, 16, v75
	v_and_b32_e32 v75, 0xffff0000, v75
	v_pk_add_f32 v[70:71], v[70:71], v[72:73]
	v_pk_add_f32 v[68:69], v[68:69], v[76:77]
	v_pk_add_f32 v[72:73], v[66:67], v[74:75]
	v_pk_add_f32 v[74:75], v[64:65], v[78:79]
	v_mul_f32_e32 v64, v69, v69
	v_mul_f32_e32 v65, v71, v71
	v_mul_f32_e32 v66, v75, v75
	v_mul_f32_e32 v67, v73, v73
	v_fmac_f32_e32 v64, v68, v68
	v_fmac_f32_e32 v65, v70, v70
	v_fmac_f32_e32 v66, v74, v74
	v_fmac_f32_e32 v67, v72, v72
	v_add_f32_e32 v64, v64, v65
	v_add_f32_e32 v65, v66, v67
	v_add_f32_e32 v64, v64, v65
	v_add_f32_e32 v64, v82, v64
	v_mov_b32_e32 v65, v64
	v_cvt_pk_bf16_f32 v66, v68, v69
	v_cvt_pk_bf16_f32 v67, v70, v71
	v_cvt_pk_bf16_f32 v68, v74, v75
	v_cvt_pk_bf16_f32 v69, v72, v73
	v_permlane16_swap_b32_e32 v64, v65
	v_add_f32_e32 v64, v64, v65
	v_mov_b32_e32 v65, v64
	flat_store_dwordx4 v[86:87], v[66:69] offset:256
	s_nop 0
	v_permlane32_swap_b32_e32 v64, v65
	s_and_saveexec_b64 s[6:7], s[0:1]
	s_cbranch_execz .LBB0_1624
	v_lshl_add_u64 v[66:67], v[80:81], 2, s[14:15]
	s_nop 0
	v_add_f32_e32 v64, v64, v65
	flat_atomic_add_f32 v[66:67], v64
.LBB0_1624:
	s_or_b64 exec, exec, s[6:7]
	v_add_u32_e32 v64, 0x80, v146
	s_waitcnt lgkmcnt(0)
	v_ashrrev_i32_e32 v65, 31, v64
	v_lshlrev_b64 v[66:67], 10, v[64:65]
	v_lshl_add_u64 v[66:67], v[66:67], 0, v[144:145]
	v_lshlrev_b64 v[70:71], 1, v[66:67]
	v_lshl_add_u64 v[72:73], s[50:51], 0, v[70:71]
	global_load_dwordx4 v[66:69], v[72:73], off
	v_lshl_add_u64 v[70:71], s[8:9], 0, v[70:71]
	s_waitcnt vmcnt(0)
	v_lshlrev_b32_e32 v74, 16, v66
	v_and_b32_e32 v75, 0xffff0000, v66
	v_lshlrev_b32_e32 v66, 16, v67
	v_and_b32_e32 v67, 0xffff0000, v67
	v_lshlrev_b32_e32 v76, 16, v68
	v_and_b32_e32 v77, 0xffff0000, v68
	v_lshlrev_b32_e32 v68, 16, v69
	v_and_b32_e32 v69, 0xffff0000, v69
	v_pk_add_f32 v[62:63], v[62:63], v[66:67]
	v_pk_add_f32 v[60:61], v[60:61], v[74:75]
	v_pk_add_f32 v[66:67], v[58:59], v[68:69]
	v_pk_add_f32 v[68:69], v[56:57], v[76:77]
	v_cvt_pk_bf16_f32 v56, v60, v61
	v_cvt_pk_bf16_f32 v57, v62, v63
	v_cvt_pk_bf16_f32 v58, v68, v69
	v_cvt_pk_bf16_f32 v59, v66, v67
	flat_store_dwordx4 v[70:71], v[56:59]
	global_load_dwordx4 v[56:59], v[72:73], off offset:256
	v_mul_f32_e32 v61, v61, v61
	v_mul_f32_e32 v63, v63, v63
	v_mul_f32_e32 v69, v69, v69
	v_mul_f32_e32 v67, v67, v67
	v_fmac_f32_e32 v61, v60, v60
	v_fmac_f32_e32 v63, v62, v62
	v_fmac_f32_e32 v69, v68, v68
	v_fmac_f32_e32 v67, v66, v66
	v_add_f32_e32 v60, v61, v63
	v_add_f32_e32 v61, v69, v67
	v_add_f32_e32 v66, v60, v61
	s_waitcnt vmcnt(0)
	v_lshlrev_b32_e32 v60, 16, v56
	v_and_b32_e32 v61, 0xffff0000, v56
	v_lshlrev_b32_e32 v56, 16, v57
	v_and_b32_e32 v57, 0xffff0000, v57
	v_lshlrev_b32_e32 v62, 16, v58
	v_and_b32_e32 v63, 0xffff0000, v58
	v_lshlrev_b32_e32 v58, 16, v59
	v_and_b32_e32 v59, 0xffff0000, v59
	v_pk_add_f32 v[54:55], v[54:55], v[56:57]
	v_pk_add_f32 v[52:53], v[52:53], v[60:61]
	v_pk_add_f32 v[56:57], v[50:51], v[58:59]
	v_pk_add_f32 v[58:59], v[48:49], v[62:63]
	v_mul_f32_e32 v48, v53, v53
	v_mul_f32_e32 v49, v55, v55
	v_mul_f32_e32 v50, v59, v59
	v_mul_f32_e32 v51, v57, v57
	v_fmac_f32_e32 v48, v52, v52
	v_fmac_f32_e32 v49, v54, v54
	v_fmac_f32_e32 v50, v58, v58
	v_fmac_f32_e32 v51, v56, v56
	v_add_f32_e32 v48, v48, v49
	v_add_f32_e32 v49, v50, v51
	v_add_f32_e32 v48, v48, v49
	v_add_f32_e32 v48, v66, v48
	v_mov_b32_e32 v49, v48
	v_cvt_pk_bf16_f32 v50, v52, v53
	v_cvt_pk_bf16_f32 v51, v54, v55
	v_cvt_pk_bf16_f32 v52, v58, v59
	v_cvt_pk_bf16_f32 v53, v56, v57
	v_permlane16_swap_b32_e32 v48, v49
	v_add_f32_e32 v48, v48, v49
	v_mov_b32_e32 v49, v48
	flat_store_dwordx4 v[70:71], v[50:53] offset:256
	s_nop 0
	v_permlane32_swap_b32_e32 v48, v49
	s_and_saveexec_b64 s[6:7], s[0:1]
	s_cbranch_execz .LBB0_1626
	v_lshl_add_u64 v[50:51], v[64:65], 2, s[14:15]
	s_nop 0
	v_add_f32_e32 v48, v48, v49
	flat_atomic_add_f32 v[50:51], v48
.LBB0_1626:
	s_or_b64 exec, exec, s[6:7]
	v_add_u32_e32 v48, 0x90, v146
	s_waitcnt lgkmcnt(0)
	v_ashrrev_i32_e32 v49, 31, v48
	v_lshlrev_b64 v[50:51], 10, v[48:49]
	v_lshl_add_u64 v[50:51], v[50:51], 0, v[144:145]
	v_lshlrev_b64 v[54:55], 1, v[50:51]
	v_lshl_add_u64 v[56:57], s[50:51], 0, v[54:55]
	global_load_dwordx4 v[50:53], v[56:57], off
	v_lshl_add_u64 v[54:55], s[8:9], 0, v[54:55]
	s_waitcnt vmcnt(0)
	v_lshlrev_b32_e32 v58, 16, v50
	v_and_b32_e32 v59, 0xffff0000, v50
	v_lshlrev_b32_e32 v50, 16, v51
	v_and_b32_e32 v51, 0xffff0000, v51
	v_lshlrev_b32_e32 v60, 16, v52
	v_and_b32_e32 v61, 0xffff0000, v52
	v_lshlrev_b32_e32 v52, 16, v53
	v_and_b32_e32 v53, 0xffff0000, v53
	v_pk_add_f32 v[46:47], v[46:47], v[50:51]
	v_pk_add_f32 v[44:45], v[44:45], v[58:59]
	v_pk_add_f32 v[50:51], v[42:43], v[52:53]
	v_pk_add_f32 v[52:53], v[40:41], v[60:61]
	v_cvt_pk_bf16_f32 v40, v44, v45
	v_cvt_pk_bf16_f32 v41, v46, v47
	v_cvt_pk_bf16_f32 v42, v52, v53
	v_cvt_pk_bf16_f32 v43, v50, v51
	flat_store_dwordx4 v[54:55], v[40:43]
	global_load_dwordx4 v[40:43], v[56:57], off offset:256
	v_mul_f32_e32 v45, v45, v45
	v_mul_f32_e32 v47, v47, v47
	v_mul_f32_e32 v53, v53, v53
	v_mul_f32_e32 v51, v51, v51
	v_fmac_f32_e32 v45, v44, v44
	v_fmac_f32_e32 v47, v46, v46
	v_fmac_f32_e32 v53, v52, v52
	v_fmac_f32_e32 v51, v50, v50
	v_add_f32_e32 v44, v45, v47
	v_add_f32_e32 v45, v53, v51
	v_add_f32_e32 v50, v44, v45
	s_waitcnt vmcnt(0)
	v_lshlrev_b32_e32 v44, 16, v40
	v_and_b32_e32 v45, 0xffff0000, v40
	v_lshlrev_b32_e32 v40, 16, v41
	v_and_b32_e32 v41, 0xffff0000, v41
	v_lshlrev_b32_e32 v46, 16, v42
	v_and_b32_e32 v47, 0xffff0000, v42
	v_lshlrev_b32_e32 v42, 16, v43
	v_and_b32_e32 v43, 0xffff0000, v43
	v_pk_add_f32 v[38:39], v[38:39], v[40:41]
	v_pk_add_f32 v[36:37], v[36:37], v[44:45]
	v_pk_add_f32 v[40:41], v[34:35], v[42:43]
	v_pk_add_f32 v[42:43], v[32:33], v[46:47]
	v_mul_f32_e32 v32, v37, v37
	v_mul_f32_e32 v33, v39, v39
	v_mul_f32_e32 v34, v43, v43
	v_mul_f32_e32 v35, v41, v41
	v_fmac_f32_e32 v32, v36, v36
	v_fmac_f32_e32 v33, v38, v38
	v_fmac_f32_e32 v34, v42, v42
	v_fmac_f32_e32 v35, v40, v40
	v_add_f32_e32 v32, v32, v33
	v_add_f32_e32 v33, v34, v35
	v_add_f32_e32 v32, v32, v33
	v_add_f32_e32 v32, v50, v32
	v_mov_b32_e32 v33, v32
	v_cvt_pk_bf16_f32 v34, v36, v37
	v_cvt_pk_bf16_f32 v35, v38, v39
	v_cvt_pk_bf16_f32 v36, v42, v43
	v_cvt_pk_bf16_f32 v37, v40, v41
	v_permlane16_swap_b32_e32 v32, v33
	v_add_f32_e32 v32, v32, v33
	v_mov_b32_e32 v33, v32
	flat_store_dwordx4 v[54:55], v[34:37] offset:256
	s_nop 0
	v_permlane32_swap_b32_e32 v32, v33
	s_and_saveexec_b64 s[6:7], s[0:1]
	s_cbranch_execz .LBB0_1628
	v_lshl_add_u64 v[34:35], v[48:49], 2, s[14:15]
	s_nop 0
	v_add_f32_e32 v32, v32, v33
	flat_atomic_add_f32 v[34:35], v32
.LBB0_1628:
	s_or_b64 exec, exec, s[6:7]
	v_add_u32_e32 v32, 0xa0, v146
	s_waitcnt lgkmcnt(0)
	v_ashrrev_i32_e32 v33, 31, v32
	v_lshlrev_b64 v[34:35], 10, v[32:33]
	v_lshl_add_u64 v[34:35], v[34:35], 0, v[144:145]
	v_lshlrev_b64 v[38:39], 1, v[34:35]
	v_lshl_add_u64 v[40:41], s[50:51], 0, v[38:39]
	global_load_dwordx4 v[34:37], v[40:41], off
	v_lshl_add_u64 v[38:39], s[8:9], 0, v[38:39]
	s_waitcnt vmcnt(0)
	v_lshlrev_b32_e32 v42, 16, v34
	v_and_b32_e32 v43, 0xffff0000, v34
	v_lshlrev_b32_e32 v34, 16, v35
	v_and_b32_e32 v35, 0xffff0000, v35
	v_lshlrev_b32_e32 v44, 16, v36
	v_and_b32_e32 v45, 0xffff0000, v36
	v_lshlrev_b32_e32 v36, 16, v37
	v_and_b32_e32 v37, 0xffff0000, v37
	v_pk_add_f32 v[30:31], v[30:31], v[34:35]
	v_pk_add_f32 v[28:29], v[28:29], v[42:43]
	v_pk_add_f32 v[34:35], v[26:27], v[36:37]
	v_pk_add_f32 v[36:37], v[24:25], v[44:45]
	v_cvt_pk_bf16_f32 v24, v28, v29
	v_cvt_pk_bf16_f32 v25, v30, v31
	v_cvt_pk_bf16_f32 v26, v36, v37
	v_cvt_pk_bf16_f32 v27, v34, v35
	flat_store_dwordx4 v[38:39], v[24:27]
	global_load_dwordx4 v[24:27], v[40:41], off offset:256
	v_mul_f32_e32 v29, v29, v29
	v_mul_f32_e32 v31, v31, v31
	v_mul_f32_e32 v37, v37, v37
	v_mul_f32_e32 v35, v35, v35
	v_fmac_f32_e32 v29, v28, v28
	v_fmac_f32_e32 v31, v30, v30
	v_fmac_f32_e32 v37, v36, v36
	v_fmac_f32_e32 v35, v34, v34
	v_add_f32_e32 v28, v29, v31
	v_add_f32_e32 v29, v37, v35
	v_add_f32_e32 v34, v28, v29
	s_waitcnt vmcnt(0)
	v_lshlrev_b32_e32 v28, 16, v24
	v_and_b32_e32 v29, 0xffff0000, v24
	v_lshlrev_b32_e32 v24, 16, v25
	v_and_b32_e32 v25, 0xffff0000, v25
	v_lshlrev_b32_e32 v30, 16, v26
	v_and_b32_e32 v31, 0xffff0000, v26
	v_lshlrev_b32_e32 v26, 16, v27
	v_and_b32_e32 v27, 0xffff0000, v27
	v_pk_add_f32 v[22:23], v[22:23], v[24:25]
	v_pk_add_f32 v[20:21], v[20:21], v[28:29]
	v_pk_add_f32 v[24:25], v[18:19], v[26:27]
	v_pk_add_f32 v[26:27], v[16:17], v[30:31]
	v_mul_f32_e32 v16, v21, v21
	v_mul_f32_e32 v17, v23, v23
	v_mul_f32_e32 v18, v27, v27
	v_mul_f32_e32 v19, v25, v25
	v_fmac_f32_e32 v16, v20, v20
	v_fmac_f32_e32 v17, v22, v22
	v_fmac_f32_e32 v18, v26, v26
	v_fmac_f32_e32 v19, v24, v24
	v_add_f32_e32 v16, v16, v17
	v_add_f32_e32 v17, v18, v19
	v_add_f32_e32 v16, v16, v17
	v_add_f32_e32 v16, v34, v16
	v_mov_b32_e32 v17, v16
	v_cvt_pk_bf16_f32 v18, v20, v21
	v_cvt_pk_bf16_f32 v19, v22, v23
	v_cvt_pk_bf16_f32 v20, v26, v27
	v_cvt_pk_bf16_f32 v21, v24, v25
	v_permlane16_swap_b32_e32 v16, v17
	v_add_f32_e32 v16, v16, v17
	v_mov_b32_e32 v17, v16
	flat_store_dwordx4 v[38:39], v[18:21] offset:256
	s_nop 0
	v_permlane32_swap_b32_e32 v16, v17
	s_and_saveexec_b64 s[6:7], s[0:1]
	s_cbranch_execz .LBB0_1630
	v_lshl_add_u64 v[18:19], v[32:33], 2, s[14:15]
	s_nop 0
	v_add_f32_e32 v16, v16, v17
	flat_atomic_add_f32 v[18:19], v16
.LBB0_1630:
	s_or_b64 exec, exec, s[6:7]
	v_add_u32_e32 v16, 0xb0, v146
	s_waitcnt lgkmcnt(0)
	v_ashrrev_i32_e32 v17, 31, v16
	v_lshlrev_b64 v[18:19], 10, v[16:17]
	v_lshl_add_u64 v[18:19], v[18:19], 0, v[144:145]
	v_lshlrev_b64 v[22:23], 1, v[18:19]
	v_lshl_add_u64 v[24:25], s[50:51], 0, v[22:23]
	global_load_dwordx4 v[18:21], v[24:25], off
	v_lshl_add_u64 v[22:23], s[8:9], 0, v[22:23]
	s_waitcnt vmcnt(0)
	v_lshlrev_b32_e32 v26, 16, v18
	v_and_b32_e32 v27, 0xffff0000, v18
	v_lshlrev_b32_e32 v18, 16, v19
	v_and_b32_e32 v19, 0xffff0000, v19
	v_lshlrev_b32_e32 v28, 16, v20
	v_and_b32_e32 v29, 0xffff0000, v20
	v_lshlrev_b32_e32 v20, 16, v21
	v_and_b32_e32 v21, 0xffff0000, v21
	v_pk_add_f32 v[14:15], v[14:15], v[18:19]
	v_pk_add_f32 v[12:13], v[12:13], v[26:27]
	v_pk_add_f32 v[18:19], v[10:11], v[20:21]
	v_pk_add_f32 v[20:21], v[8:9], v[28:29]
	v_cvt_pk_bf16_f32 v8, v12, v13
	v_cvt_pk_bf16_f32 v9, v14, v15
	v_cvt_pk_bf16_f32 v10, v20, v21
	v_cvt_pk_bf16_f32 v11, v18, v19
	flat_store_dwordx4 v[22:23], v[8:11]
	global_load_dwordx4 v[8:11], v[24:25], off offset:256
	v_mul_f32_e32 v13, v13, v13
	v_mul_f32_e32 v15, v15, v15
	v_mul_f32_e32 v21, v21, v21
	v_mul_f32_e32 v19, v19, v19
	v_fmac_f32_e32 v13, v12, v12
	v_fmac_f32_e32 v15, v14, v14
	v_fmac_f32_e32 v21, v20, v20
	v_fmac_f32_e32 v19, v18, v18
	v_add_f32_e32 v12, v13, v15
	v_add_f32_e32 v13, v21, v19
	v_add_f32_e32 v18, v12, v13
	s_waitcnt vmcnt(0)
	v_lshlrev_b32_e32 v12, 16, v8
	v_and_b32_e32 v13, 0xffff0000, v8
	v_lshlrev_b32_e32 v8, 16, v9
	v_and_b32_e32 v9, 0xffff0000, v9
	v_lshlrev_b32_e32 v14, 16, v10
	v_and_b32_e32 v15, 0xffff0000, v10
	v_lshlrev_b32_e32 v10, 16, v11
	v_and_b32_e32 v11, 0xffff0000, v11
	v_pk_add_f32 v[6:7], v[6:7], v[8:9]
	v_pk_add_f32 v[4:5], v[4:5], v[12:13]
	v_pk_add_f32 v[8:9], v[2:3], v[10:11]
	v_pk_add_f32 v[10:11], v[0:1], v[14:15]
	v_mul_f32_e32 v0, v5, v5
	v_mul_f32_e32 v1, v7, v7
	v_mul_f32_e32 v2, v11, v11
	v_mul_f32_e32 v3, v9, v9
	v_fmac_f32_e32 v0, v4, v4
	v_fmac_f32_e32 v1, v6, v6
	v_fmac_f32_e32 v2, v10, v10
	v_fmac_f32_e32 v3, v8, v8
	v_add_f32_e32 v0, v0, v1
	v_add_f32_e32 v1, v2, v3
	v_add_f32_e32 v0, v0, v1
	v_add_f32_e32 v0, v18, v0
	v_mov_b32_e32 v1, v0
	v_cvt_pk_bf16_f32 v2, v4, v5
	v_cvt_pk_bf16_f32 v3, v6, v7
	v_cvt_pk_bf16_f32 v4, v10, v11
	v_cvt_pk_bf16_f32 v5, v8, v9
	v_permlane16_swap_b32_e32 v0, v1
	v_add_f32_e32 v0, v0, v1
	v_mov_b32_e32 v1, v0
	flat_store_dwordx4 v[22:23], v[2:5] offset:256
	s_nop 0
	v_permlane32_swap_b32_e32 v0, v1
	s_and_saveexec_b64 s[6:7], s[0:1]
	s_cbranch_execz .LBB0_1632
	v_lshl_add_u64 v[2:3], v[16:17], 2, s[14:15]
	s_nop 0
	v_add_f32_e32 v0, v0, v1
	flat_atomic_add_f32 v[2:3], v0
